# wave priorities: indexer scoring loop high, attention non-loop code base priority 1
# speedup vs baseline: 1.2487x; 1.0036x over previous
.LBB0_615:
	s_cmp_lt_i32 s49, 0
	s_cbranch_scc1 .LBB0_641
	s_cmp_gt_u32 s49, 31
	s_mov_b64 s[28:29], -1
	s_cbranch_scc0 .LBB0_791
	s_and_b32 s28, s52, 1
	v_writelane_b32 v248, s63, 25
	s_lshl_b32 s29, s49, 3
	s_lshl_b32 s28, s28, 2
	v_writelane_b32 v248, s49, 27
	s_or_b32 s28, s29, s28
	s_add_i32 s29, s28, 0xffffff00
	s_sub_i32 s30, 0x8fc, s28
	v_writelane_b32 v248, s52, 24
	s_lshr_b32 s34, s52, 1
	v_readfirstlane_b32 s28, v104
	s_lshr_b32 s28, s28, 6
	v_writelane_b32 v248, s30, 22
	s_lshl_b32 s53, s30, 1
	s_lshl_b32 s52, s34, 12
	v_writelane_b32 v248, s34, 28
	s_cmpk_lt_u32 s29, 0x77d
	s_mov_b64 s[34:35], -1
	s_cbranch_scc0 .LBB0_784
	s_or_b32 s29, s53, s52
	v_or_b32_e32 v0, s29, v219
	v_lshlrev_b32_e32 v122, 7, v0
	v_or_b32_e32 v8, s29, v113
	s_or_b32 s29, s29, 4
	v_lshl_add_u64 v[4:5], v[118:119], 0, v[122:123]
	v_or_b32_e32 v122, s29, v219
	v_lshlrev_b64 v[12:13], 7, v[122:123]
	v_or_b32_e32 v122, s29, v113
	v_readlane_b32 s29, v248, 22
	s_lshr_b32 s29, s29, 3
	s_sub_i32 s29, s29, s28
	v_readlane_b32 s36, v250, 0
	s_add_i32 s29, s29, 4
	v_readlane_b32 s37, v250, 1
	v_readlane_b32 s30, v248, 28
	s_ashr_i32 s34, s29, 2
	s_mov_b32 s29, s31
	s_lshl_b32 s30, s30, 19
	s_add_i32 s35, s34, -1
	s_lshl_b64 s[36:37], s[28:29], 11
	s_cmp_gt_i32 s34, 1
	s_cselect_b32 s29, 4, 0
	v_lshl_add_u64 v[140:141], v[128:129], 0, s[30:31]
	s_add_i32 s30, s29, s28
	s_max_i32 s29, s35, 0
	v_lshl_add_u64 v[24:25], v[140:141], 0, s[36:37]
	s_lshl_b64 s[36:37], s[30:31], 11
	s_min_i32 s30, s29, 2
	v_readlane_b32 s38, v250, 2
	v_readlane_b32 s39, v250, 3
	s_lshl_b32 s30, s30, 2
	v_lshlrev_b32_e32 v8, 4, v8
	v_lshl_add_u64 v[16:17], v[118:119], 0, v[12:13]
	v_lshl_add_u64 v[20:21], v[122:123], 4, s[38:39]
	s_add_i32 s30, s30, s28
	global_load_dwordx4 v[0:3], v[4:5], off
	s_nop 0
	global_load_dwordx4 v[4:7], v[4:5], off offset:64
	v_readlane_b32 s40, v250, 4
	global_load_dwordx4 v[8:11], v8, s[38:39]
	s_nop 0
	global_load_dwordx4 v[12:15], v[16:17], off
	s_nop 0
	global_load_dwordx4 v[16:19], v[16:17], off offset:64
	v_readlane_b32 s41, v250, 5
	global_load_dwordx4 v[20:23], v[20:21], off
	s_nop 0
	global_load_dwordx4 v[92:95], v[24:25], off
	global_load_dwordx4 v[88:91], v[24:25], off offset:1024
	v_lshl_add_u64 v[24:25], v[140:141], 0, s[36:37]
	s_lshl_b64 s[36:37], s[30:31], 11
	s_min_i32 s30, s29, 3
	s_lshl_b32 s30, s30, 2
	s_add_i32 s30, s30, s28
	global_load_dwordx4 v[76:79], v[24:25], off
	global_load_dwordx4 v[72:75], v[24:25], off offset:1024
	v_lshl_add_u64 v[24:25], v[140:141], 0, s[36:37]
	s_lshl_b64 s[36:37], s[30:31], 11
	s_min_i32 s30, s29, 4
	s_lshl_b32 s30, s30, 2
	s_add_i32 s30, s30, s28
	global_load_dwordx4 v[60:63], v[24:25], off
	global_load_dwordx4 v[56:59], v[24:25], off offset:1024
	v_lshl_add_u64 v[24:25], v[140:141], 0, s[36:37]
	s_lshl_b64 s[36:37], s[30:31], 11
	s_min_i32 s30, s29, 5
	s_lshl_b32 s30, s30, 2
	s_add_i32 s30, s30, s28
	global_load_dwordx4 v[44:47], v[24:25], off
	global_load_dwordx4 v[40:43], v[24:25], off offset:1024
	v_lshl_add_u64 v[24:25], v[140:141], 0, s[36:37]
	s_lshl_b64 s[36:37], s[30:31], 11
	s_min_i32 s30, s29, 6
	s_lshl_b32 s30, s30, 2
	s_add_i32 s30, s30, s28
	v_lshl_add_u64 v[32:33], v[140:141], 0, s[36:37]
	s_lshl_b64 s[36:37], s[30:31], 11
	s_min_i32 s30, s29, 7
	s_lshl_b32 s30, s30, 2
	s_add_i32 s30, s30, s28
	global_load_dwordx4 v[28:31], v[24:25], off
	s_nop 0
	global_load_dwordx4 v[24:27], v[24:25], off offset:1024
	s_nop 0
	global_load_dwordx4 v[100:103], v[32:33], off
	global_load_dwordx4 v[96:99], v[32:33], off offset:1024
	v_lshl_add_u64 v[32:33], v[140:141], 0, s[36:37]
	s_lshl_b64 s[36:37], s[30:31], 11
	s_min_i32 s30, s29, 8
	s_lshl_b32 s30, s30, 2
	s_min_i32 s29, s29, 9
	s_add_i32 s30, s30, s28
	s_lshl_b32 s29, s29, 2
	global_load_dwordx4 v[84:87], v[32:33], off
	global_load_dwordx4 v[80:83], v[32:33], off offset:1024
	v_lshl_add_u64 v[32:33], v[140:141], 0, s[36:37]
	s_lshl_b64 s[36:37], s[30:31], 11
	s_add_i32 s30, s29, s28
	global_load_dwordx4 v[68:71], v[32:33], off
	global_load_dwordx4 v[64:67], v[32:33], off offset:1024
	v_lshl_add_u64 v[32:33], v[140:141], 0, s[36:37]
	s_lshl_b64 s[36:37], s[30:31], 11
	global_load_dwordx4 v[52:55], v[32:33], off
	global_load_dwordx4 v[48:51], v[32:33], off offset:1024
	v_lshl_add_u64 v[32:33], v[140:141], 0, s[36:37]
	global_load_dwordx4 v[36:39], v[32:33], off
	s_nop 0
	global_load_dwordx4 v[32:35], v[32:33], off offset:1024
	s_cmp_lt_i32 s34, 1
	v_readlane_b32 s42, v250, 6
	v_readlane_b32 s43, v250, 7
	s_waitcnt vmcnt(21)
	s_waitcnt vmcnt(20)
	s_cbranch_scc1 .LBB0_642
	s_add_i32 s29, s34, 4
	s_mul_hi_i32 s29, s29, 0x66666667
	s_lshr_b32 s30, s29, 31
	s_ashr_i32 s29, s29, 1
	s_add_i32 s29, s29, s30
	v_lshl_add_u32 v122, s28, 5, v218
	s_mov_b32 s36, 0
	s_mov_b32 s37, 9
	s_setprio 2
	s_branch .LBB0_621

.LBB0_642:
	s_setprio 0
	s_mov_b32 s29, 0
	s_mov_b64 s[34:35], -1
	s_waitcnt lgkmcnt(0)
	s_barrier
	s_waitcnt vmcnt(0)
	s_branch .LBB0_644

.LBB0_810:
	s_setprio 1
	s_barrier
	s_and_saveexec_b64 s[2:3], s[60:61]
	s_cbranch_execz .LBB0_814
	s_mov_b64 s[40:41], exec
	v_mbcnt_lo_u32_b32 v0, s40, 0
	v_mbcnt_hi_u32_b32 v0, s41, v0
	v_cmp_eq_u32_e32 vcc, 0, v0
	s_and_saveexec_b64 s[38:39], vcc
	s_cbranch_execz .LBB0_813
	v_readlane_b32 s33, v248, 8
	s_lshl_b32 s44, s33, 4
	v_readlane_b32 s48, v250, 0
	s_lshl_b64 s[42:43], s[44:45], 2
	v_readlane_b32 s54, v250, 6
	v_readlane_b32 s55, v250, 7
	s_add_u32 s42, s54, s42
	s_addc_u32 s43, s55, s43
	s_bcnt1_i32_b64 s33, s[40:41]
	v_mov_b32_e32 v1, s33
	global_atomic_add v1, v117, v1, s[42:43] offset:512 sc0
	v_readlane_b32 s50, v250, 2
	v_readlane_b32 s51, v250, 3
	v_readlane_b32 s50, v248, 20
	v_readlane_b32 s60, v250, 56
	v_readlane_b32 s51, v248, 21
	v_readlane_b32 s61, v250, 57
	v_readlane_b32 s49, v250, 1
	v_readlane_b32 s52, v250, 4
	v_readlane_b32 s53, v250, 5

.Lcmpa_done:
	s_waitcnt lgkmcnt(0)
	s_setprio 1
	v_add_f32_e32 v61, v54, v55
	v_add_f32_e32 v60, v56, v57
	global_load_dwordx4 v[62:65], v[154:155], off
	global_load_dwordx4 v[66:69], v[156:157], off
	global_load_dwordx4 v[70:73], v[40:41], off
	global_load_dwordx4 v[188:191], v[42:43], off
	global_load_dwordx4 v[16:19], v[32:33], off
	global_load_dwordx4 v[20:23], v[34:35], off
	global_load_dwordx4 v[24:27], v[36:37], off
	global_load_dwordx4 v[28:31], v[38:39], off
	v_and_b32_e32 v33, 64, v121
	v_xor_b32_e32 v59, 16, v121
	v_add_u32_e32 v187, 64, v33
	v_cmp_lt_i32_e32 vcc, v59, v187
	v_xor_b32_e32 v162, 32, v121
	v_xor_b32_e32 v163, 1, v121
	v_cndmask_b32_e32 v59, v121, v59, vcc
	v_lshlrev_b32_e32 v182, 2, v59
	ds_bpermute_b32 v75, v182, v61
	ds_bpermute_b32 v74, v182, v60
	v_cmp_lt_i32_e32 vcc, v162, v187
	v_xor_b32_e32 v186, 2, v121
	s_mul_i32 s42, s33, 0x1020
	v_cndmask_b32_e32 v162, v121, v162, vcc
	v_lshlrev_b32_e32 v183, 2, v162
	s_waitcnt lgkmcnt(0)
	v_pk_add_f32 v[60:61], v[60:61], v[74:75]
	ds_bpermute_b32 v75, v183, v61
	ds_bpermute_b32 v74, v183, v60
	v_cmp_lt_i32_e32 vcc, v163, v187
	v_mov_b32_e32 v32, 0
	s_movk_i32 s47, 0x4000
	v_cndmask_b32_e32 v162, v121, v163, vcc
	s_waitcnt lgkmcnt(0)
	v_pk_add_f32 v[60:61], v[60:61], v[74:75]
	v_cmp_lt_i32_e32 vcc, v186, v187
	v_log_f32_e32 v74, v61
	v_log_f32_e32 v75, v60
	v_cndmask_b32_e32 v163, v121, v186, vcc
	v_cmp_lt_f32_e32 vcc, 0, v61
	s_movk_i32 s43, 0x1000
	s_mov_b32 s33, 2
	v_cndmask_b32_e64 v186, 0, -v74, vcc
	v_cmp_lt_f32_e32 vcc, 0, v60
	s_not_b32 s39, s38
	v_add_u32_e32 v159, s42, v174
	v_add_u32_e32 v160, s42, v175
	v_add_u32_e32 v161, s42, v176
	v_mov_b32_e32 v33, v32
	v_mov_b32_e32 v34, v32
	v_mov_b32_e32 v35, v32
	v_mov_b32_e32 v36, v32
	v_mov_b32_e32 v37, v32
	v_mov_b32_e32 v38, v32
	v_mov_b32_e32 v39, v32
	v_mov_b32_e32 v40, v32
	v_mov_b32_e32 v41, v32
	v_mov_b32_e32 v42, v32
	v_mov_b32_e32 v43, v32
	v_mov_b32_e32 v44, v32
	v_mov_b32_e32 v45, v32
	v_mov_b32_e32 v46, v32
	v_mov_b32_e32 v47, v32
	v_mov_b32_e32 v48, v32
	v_mov_b32_e32 v49, v32
	v_mov_b32_e32 v50, v32
	v_mov_b32_e32 v51, v32
	v_mov_b32_e32 v52, v32
	v_mov_b32_e32 v53, v32
	v_mov_b32_e32 v54, v32
	v_mov_b32_e32 v55, v32
	v_mov_b32_e32 v56, v32
	v_mov_b32_e32 v57, v32
	v_mov_b32_e32 v58, v32
	v_mov_b32_e32 v59, v32
	v_lshlrev_b32_e32 v162, 2, v162
	v_lshlrev_b32_e32 v163, 2, v163
	v_cndmask_b32_e64 v187, 0, -v75, vcc
	v_mov_b32_e32 v60, v32
	v_mov_b32_e32 v61, v32
	v_readlane_b32 s50, v250, 56
	v_readlane_b32 s51, v250, 57
	s_waitcnt vmcnt(7)
	ds_write_b128 v127, v[62:65]
	s_waitcnt vmcnt(6)
	ds_write_b128 v127, v[66:69] offset:18432
	s_waitcnt vmcnt(5)
	ds_write_b128 v127, v[70:73] offset:4608
	s_waitcnt vmcnt(4)
	ds_write_b128 v127, v[188:191] offset:23040
	v_mov_b32_e32 v62, v32
	v_mov_b32_e32 v63, v32
	s_waitcnt lgkmcnt(0)
	s_barrier
	s_branch .LBB0_838

.LBB0_868:
	s_and_b32 s44, s2, 1
	s_xor_b32 s49, s44, 1
	s_mulk_i32 s49, 0x2400
	s_mulk_i32 s44, 0x2400
	v_add_u32_e32 v80, s44, v129
	v_add_u32_e32 v113, s49, v127
	v_add_u32_e32 v76, s44, v167
	ds_read_b128 v[202:205], v80 offset:4608
	ds_read_b128 v[206:209], v80 offset:4672
	ds_read_b128 v[210:213], v80 offset:6912
	ds_read_b128 v[218:221], v80 offset:6976
	v_lshrrev_b64 v[246:247], s2, v[72:73]
	v_lshrrev_b64 v[244:245], s2, v[74:75]
	v_add_u32_e32 v80, s49, v129
	v_not_b32_e32 v246, v246
	v_not_b32_e32 v247, v244
	v_bfe_i32 v246, v246, 0, 1
	v_bfe_i32 v247, v247, 0, 1
	v_and_b32_e32 v238, 0xf149f2ca, v246
	v_and_b32_e32 v242, 0xf149f2ca, v247
	v_and_b32_e32 v239, 0xf149f2ca, v246
	v_and_b32_e32 v243, 0xf149f2ca, v247
	v_and_b32_e32 v240, 0xf149f2ca, v246
	v_and_b32_e32 v244, 0xf149f2ca, v247
	v_and_b32_e32 v241, 0xf149f2ca, v246
	v_and_b32_e32 v245, 0xf149f2ca, v247
	s_waitcnt lgkmcnt(5)
	v_mfma_f32_16x16x32_bf16 v[64:67], v[186:189], v[0:3], v[238:241]
	v_mfma_f32_16x16x32_bf16 v[68:71], v[186:189], v[8:11], v[242:245]
	v_mfma_f32_16x16x32_bf16 v[222:225], v[194:197], v[0:3], v[238:241]
	v_mfma_f32_16x16x32_bf16 v[226:229], v[194:197], v[8:11], v[242:245]
	s_waitcnt vmcnt(2)
	ds_write_b128 v113, v[52:55]
	ds_write_b128 v113, v[48:51] offset:18432
	s_waitcnt lgkmcnt(6)
	v_mfma_f32_16x16x32_bf16 v[64:67], v[190:193], v[4:7], v[64:67]
	v_mfma_f32_16x16x32_bf16 v[68:71], v[190:193], v[12:15], v[68:71]
	v_mfma_f32_16x16x32_bf16 v[222:225], v[198:201], v[4:7], v[222:225]
	v_mfma_f32_16x16x32_bf16 v[226:229], v[198:201], v[12:15], v[226:229]
	s_waitcnt vmcnt(0)
	ds_write_b128 v113, v[56:59] offset:4608
	ds_write_b128 v113, v[60:63] offset:23040
	s_add_i32 s48, s2, 2
	s_min_i32 s48, s48, s47
	s_lshl_b32 s44, s48, 6
	s_lshl_b64 s[48:49], s[44:45], 7
	v_lshl_add_u64 v[52:53], v[158:159], 0, s[48:49]
	v_lshl_add_u64 v[48:49], s[44:45], 1, v[156:157]
	s_or_b32 s44, s44, 32
	s_lshl_b64 s[48:49], s[44:45], 7
	global_load_dwordx4 v[52:55], v[52:53], off
	v_lshl_add_u64 v[56:57], v[158:159], 0, s[48:49]
	v_add_co_u32_e32 v60, vcc, s50, v48
	s_nop 0
	v_addc_co_u32_e32 v61, vcc, 0, v49, vcc
	global_load_dwordx4 v[48:51], v[48:49], off
	global_load_dwordx4 v[56:59], v[56:57], off
	global_load_dwordx4 v[60:63], v[60:61], off
	ds_read_b64 v[186:187], v76 offset:18432
	ds_read_b64 v[188:189], v76 offset:18464
	ds_read_b64 v[190:191], v76 offset:20736
	ds_read_b64 v[192:193], v76 offset:20768
	ds_read_b64 v[194:195], v76 offset:23040
	ds_read_b64 v[196:197], v76 offset:23072
	ds_read_b64 v[198:199], v76 offset:25344
	s_waitcnt lgkmcnt(13)
	ds_read_b64 v[200:201], v76 offset:25376
	s_waitcnt lgkmcnt(13)
	v_mfma_f32_16x16x32_bf16 v[230:233], v[202:205], v[0:3], v[238:241]
	v_mfma_f32_16x16x32_bf16 v[234:237], v[202:205], v[8:11], v[242:245]
	v_mfma_f32_16x16x32_bf16 v[238:241], v[210:213], v[0:3], v[238:241]
	v_mfma_f32_16x16x32_bf16 v[242:245], v[210:213], v[8:11], v[242:245]
	s_waitcnt lgkmcnt(12)
	v_mfma_f32_16x16x32_bf16 v[230:233], v[206:209], v[4:7], v[230:233]
	v_mfma_f32_16x16x32_bf16 v[234:237], v[206:209], v[12:15], v[234:237]
	v_mfma_f32_16x16x32_bf16 v[238:241], v[218:221], v[4:7], v[238:241]
	v_mfma_f32_16x16x32_bf16 v[242:245], v[218:221], v[12:15], v[242:245]
	ds_read_b64 v[202:203], v76 offset:18496
	ds_read_b64 v[204:205], v76 offset:18528
	ds_read_b64 v[206:207], v76 offset:20800
	s_waitcnt lgkmcnt(13)
	ds_read_b64 v[208:209], v76 offset:20832
	ds_read_b64 v[210:211], v76 offset:23104
	s_waitcnt lgkmcnt(13)
	ds_read_b64 v[212:213], v76 offset:23136
	ds_read_b64 v[218:219], v76 offset:25408
	s_waitcnt lgkmcnt(13)
	ds_read_b64 v[220:221], v76 offset:25440
	s_setprio 0
	s_add_u32 s2, s2, 1
	s_addc_u32 s3, s3, 0
	v_exp_f32_e32 v64, v64
	v_exp_f32_e32 v68, v68
	v_exp_f32_e32 v65, v65
	v_exp_f32_e32 v69, v69
	v_exp_f32_e32 v66, v66
	v_exp_f32_e32 v70, v70
	v_exp_f32_e32 v67, v67
	v_exp_f32_e32 v71, v71
	v_pk_add_f32 v[160:161], v[160:161], v[64:65]
	v_pk_add_f32 v[162:163], v[162:163], v[68:69]
	v_pk_add_f32 v[160:161], v[160:161], v[66:67]
	v_pk_add_f32 v[162:163], v[162:163], v[70:71]
	v_exp_f32_e32 v222, v222
	v_exp_f32_e32 v226, v226
	v_exp_f32_e32 v223, v223
	v_exp_f32_e32 v227, v227
	v_exp_f32_e32 v224, v224
	v_exp_f32_e32 v228, v228
	v_exp_f32_e32 v225, v225
	v_exp_f32_e32 v229, v229
	v_pk_add_f32 v[160:161], v[160:161], v[222:223]
	v_pk_add_f32 v[162:163], v[162:163], v[226:227]
	v_pk_add_f32 v[160:161], v[160:161], v[224:225]
	v_pk_add_f32 v[162:163], v[162:163], v[228:229]
	s_waitcnt lgkmcnt(0)
	s_barrier
	v_cvt_pk_bf16_f32 v64, v64, v65
	v_cvt_pk_bf16_f32 v68, v68, v69
	v_cvt_pk_bf16_f32 v65, v66, v67
	v_cvt_pk_bf16_f32 v69, v70, v71
	v_cvt_pk_bf16_f32 v66, v222, v223
	v_cvt_pk_bf16_f32 v70, v226, v227
	v_cvt_pk_bf16_f32 v67, v224, v225
	v_cvt_pk_bf16_f32 v71, v228, v229
	v_exp_f32_e32 v230, v230
	v_exp_f32_e32 v234, v234
	v_mfma_f32_16x16x32_bf16 v[28:31], v[186:189], v[64:67], v[28:31]
	v_exp_f32_e32 v231, v231
	v_exp_f32_e32 v235, v235
	v_exp_f32_e32 v232, v232
	v_exp_f32_e32 v236, v236
	v_mfma_f32_16x16x32_bf16 v[20:23], v[186:189], v[68:71], v[20:23]
	v_exp_f32_e32 v233, v233
	v_exp_f32_e32 v237, v237
	v_pk_add_f32 v[160:161], v[160:161], v[230:231]
	v_pk_add_f32 v[162:163], v[162:163], v[234:235]
	v_mfma_f32_16x16x32_bf16 v[16:19], v[190:193], v[64:67], v[16:19]
	v_pk_add_f32 v[160:161], v[160:161], v[232:233]
	v_pk_add_f32 v[162:163], v[162:163], v[236:237]
	v_exp_f32_e32 v238, v238
	v_exp_f32_e32 v242, v242
	v_mfma_f32_16x16x32_bf16 v[24:27], v[190:193], v[68:71], v[24:27]
	v_exp_f32_e32 v239, v239
	v_exp_f32_e32 v243, v243
	v_exp_f32_e32 v240, v240
	v_exp_f32_e32 v244, v244
	v_mfma_f32_16x16x32_bf16 v[40:43], v[194:197], v[64:67], v[40:43]
	v_exp_f32_e32 v241, v241
	v_exp_f32_e32 v245, v245
	v_pk_add_f32 v[160:161], v[160:161], v[238:239]
	v_pk_add_f32 v[162:163], v[162:163], v[242:243]
	v_mfma_f32_16x16x32_bf16 v[44:47], v[194:197], v[68:71], v[44:47]
	v_pk_add_f32 v[160:161], v[160:161], v[240:241]
	v_pk_add_f32 v[162:163], v[162:163], v[244:245]
	v_cvt_pk_bf16_f32 v230, v230, v231
	v_cvt_pk_bf16_f32 v234, v234, v235
	v_mfma_f32_16x16x32_bf16 v[36:39], v[198:201], v[64:67], v[36:39]
	v_cvt_pk_bf16_f32 v231, v232, v233
	v_cvt_pk_bf16_f32 v235, v236, v237
	v_cvt_pk_bf16_f32 v232, v238, v239
	v_cvt_pk_bf16_f32 v236, v242, v243
	v_mfma_f32_16x16x32_bf16 v[32:35], v[198:201], v[68:71], v[32:35]
	v_cvt_pk_bf16_f32 v233, v240, v241
	v_cvt_pk_bf16_f32 v237, v244, v245
	ds_read_b128 v[186:189], v80 offset:0
	ds_read_b128 v[190:193], v80 offset:64
	ds_read_b128 v[194:197], v80 offset:2304
	ds_read_b128 v[198:201], v80 offset:2368
	s_setprio 2
	v_mfma_f32_16x16x32_bf16 v[28:31], v[202:205], v[230:233], v[28:31]
	v_mfma_f32_16x16x32_bf16 v[20:23], v[202:205], v[234:237], v[20:23]
	v_mfma_f32_16x16x32_bf16 v[16:19], v[206:209], v[230:233], v[16:19]
	v_mfma_f32_16x16x32_bf16 v[24:27], v[206:209], v[234:237], v[24:27]
	v_mfma_f32_16x16x32_bf16 v[40:43], v[210:213], v[230:233], v[40:43]
	v_mfma_f32_16x16x32_bf16 v[44:47], v[210:213], v[234:237], v[44:47]
	v_mfma_f32_16x16x32_bf16 v[36:39], v[218:221], v[230:233], v[36:39]
	v_mfma_f32_16x16x32_bf16 v[32:35], v[218:221], v[234:237], v[32:35]
	s_cmp_lg_u32 s46, s2
	s_cbranch_scc1 .LBB0_868
	s_waitcnt lgkmcnt(0)
	s_setprio 1
	v_add_f32_e32 v160, v160, v161
	v_add_f32_e32 v161, v162, v163
	s_waitcnt vmcnt(3)
	v_mov_b32_e32 v53, v160
	v_mov_b32_e32 v52, v161

.Lwin_done:
	s_waitcnt lgkmcnt(0)
	s_setprio 1
	v_add_f32_e32 v153, v158, v159
	v_add_f32_e32 v156, v160, v161

.LBB0_885:
	s_and_b32 s41, s39, 1
	s_xor_b32 s42, s41, 1
	s_mul_i32 s43, s42, 0x2400
	v_add_u32_e32 v199, s43, v127
	s_waitcnt vmcnt(4)
	ds_write_b128 v199, v[16:19]
	s_waitcnt vmcnt(3)
	ds_write_b128 v199, v[20:23] offset:18432
	s_waitcnt vmcnt(1)
	ds_write_b128 v199, v[24:27] offset:4608
	s_waitcnt vmcnt(0)
	ds_write_b128 v199, v[28:31] offset:23040
	v_lshl_or_b32 v217, s42, 8, v169
	ds_write_b64 v217, v[152:153] offset:53376
	v_lshl_add_u32 v217, s41, 8, v78
	s_mulk_i32 s41, 0x2400
	v_add_u32_e32 v251, s41, v129
	v_add_u32_e32 v199, s41, v131
	ds_read_b64 v[212:213], v217 offset:53376
	ds_read_b64 v[246:247], v217 offset:53408
	ds_read_b128 v[218:221], v251 offset:0
	ds_read_b128 v[222:225], v251 offset:64
	ds_read_b128 v[226:229], v251 offset:2304
	ds_read_b128 v[230:233], v251 offset:2368
	ds_read_b128 v[234:237], v251 offset:4608
	ds_read_b128 v[238:241], v251 offset:4672
	ds_read_b128 v[242:245], v251 offset:6912
	ds_read_b128 v[200:203], v251 offset:6976
	s_add_i32 s42, s39, 2
	s_min_i32 s42, s42, s38
	s_lshl_b32 s44, s42, 13
	s_lshl_b32 s46, s42, 7
	s_mov_b32 s47, s45
	s_mov_b32 s43, s45
	v_lshl_add_u64 v[16:17], v[148:149], 0, s[44:45]
	v_lshl_add_u64 v[28:29], v[150:151], 0, s[46:47]
	v_lshl_add_u64 v[152:153], s[42:43], 3, v[146:147]
	global_load_dwordx4 v[16:19], v[16:17], off
	global_load_dwordx4 v[20:23], v[28:29], off
	global_load_dwordx2 v[152:153], v[152:153], off
	s_addk_i32 s44, 0x1000
	s_add_i32 s46, s46, 0x40000
	v_lshl_add_u64 v[24:25], v[148:149], 0, s[44:45]
	v_lshl_add_u64 v[28:29], v[150:151], 0, s[46:47]
	global_load_dwordx4 v[24:27], v[24:25], off
	global_load_dwordx4 v[28:31], v[28:29], off
	s_waitcnt lgkmcnt(8)
	v_lshrrev_b32_e32 v212, v112, v212
	v_lshrrev_b32_e32 v213, v112, v213
	v_lshrrev_b32_e32 v246, v112, v246
	v_lshrrev_b32_e32 v247, v112, v247
	s_waitcnt lgkmcnt(7)
	v_mfma_f32_16x16x32_bf16 v[64:67], v[218:221], v[0:3], 0
	v_mfma_f32_16x16x32_bf16 v[68:71], v[218:221], v[8:11], 0
	ds_read_b64 v[194:195], v199 offset:18432
	ds_read_b64 v[196:197], v199 offset:18464
	s_waitcnt lgkmcnt(8)
	v_mfma_f32_16x16x32_bf16 v[64:67], v[222:225], v[4:7], v[64:67]
	v_mfma_f32_16x16x32_bf16 v[68:71], v[222:225], v[12:15], v[68:71]
	s_waitcnt lgkmcnt(7)
	v_mfma_f32_16x16x32_bf16 v[72:75], v[226:229], v[0:3], 0
	v_mfma_f32_16x16x32_bf16 v[156:159], v[226:229], v[8:11], 0
	ds_read_b64 v[204:205], v199 offset:20736
	ds_read_b64 v[206:207], v199 offset:20768
	s_waitcnt lgkmcnt(8)
	v_mfma_f32_16x16x32_bf16 v[72:75], v[230:233], v[4:7], v[72:75]
	v_mfma_f32_16x16x32_bf16 v[156:159], v[230:233], v[12:15], v[156:159]
	s_waitcnt lgkmcnt(7)
	v_mfma_f32_16x16x32_bf16 v[160:163], v[234:237], v[0:3], 0
	v_mfma_f32_16x16x32_bf16 v[182:185], v[234:237], v[8:11], 0
	ds_read_b64 v[208:209], v199 offset:23040
	ds_read_b64 v[210:211], v199 offset:23072
	s_waitcnt lgkmcnt(8)
	v_mfma_f32_16x16x32_bf16 v[160:163], v[238:241], v[4:7], v[160:163]
	v_mfma_f32_16x16x32_bf16 v[182:185], v[238:241], v[12:15], v[182:185]
	ds_read_b64 v[218:219], v199 offset:18496
	ds_read_b64 v[220:221], v199 offset:18528
	ds_read_b64 v[222:223], v199 offset:20800
	ds_read_b64 v[224:225], v199 offset:20832
	s_waitcnt lgkmcnt(11)
	v_mfma_f32_16x16x32_bf16 v[186:189], v[242:245], v[0:3], 0
	v_mfma_f32_16x16x32_bf16 v[190:193], v[242:245], v[8:11], 0
	ds_read_b64 v[84:85], v199 offset:25344
	ds_read_b64 v[86:87], v199 offset:25376
	s_waitcnt lgkmcnt(12)
	v_mfma_f32_16x16x32_bf16 v[186:189], v[200:203], v[4:7], v[186:189]
	v_mfma_f32_16x16x32_bf16 v[190:193], v[200:203], v[12:15], v[190:193]
	ds_read_b64 v[226:227], v199 offset:23104
	ds_read_b64 v[228:229], v199 offset:23136
	ds_read_b64 v[230:231], v199 offset:25408
	s_waitcnt lgkmcnt(13)
	ds_read_b64 v[232:233], v199 offset:25440
	s_setprio 0
	s_waitcnt lgkmcnt(0)
	s_barrier
	v_exp_f32_e32 v64, v64
	v_exp_f32_e32 v68, v68
	v_exp_f32_e32 v65, v65
	v_exp_f32_e32 v69, v69
	v_bfe_i32 v82, v212, 0, 1
	v_bfe_i32 v145, v246, 0, 1
	v_exp_f32_e32 v66, v66
	v_exp_f32_e32 v70, v70
	v_and_b32_e32 v64, v82, v64
	v_and_b32_e32 v68, v145, v68
	v_bfe_i32 v113, v212, 1, 1
	v_bfe_i32 v198, v246, 1, 1
	v_exp_f32_e32 v67, v67
	v_exp_f32_e32 v71, v71
	v_and_b32_e32 v65, v113, v65
	v_and_b32_e32 v69, v198, v69
	v_add_f32_e32 v155, v155, v64
	v_add_f32_e32 v154, v154, v68
	v_bfe_i32 v82, v212, 2, 1
	v_bfe_i32 v145, v246, 2, 1
	v_and_b32_e32 v66, v82, v66
	v_and_b32_e32 v70, v145, v70
	v_add_f32_e32 v155, v155, v65
	v_add_f32_e32 v154, v154, v69
	v_bfe_i32 v113, v212, 3, 1
	v_bfe_i32 v198, v246, 3, 1
	v_and_b32_e32 v67, v113, v67
	v_and_b32_e32 v71, v198, v71
	v_add_f32_e32 v155, v155, v66
	v_add_f32_e32 v154, v154, v70
	v_add_f32_e32 v155, v155, v67
	v_add_f32_e32 v154, v154, v71
	v_exp_f32_e32 v72, v72
	v_exp_f32_e32 v156, v156
	v_exp_f32_e32 v73, v73
	v_exp_f32_e32 v157, v157
	v_bfe_i32 v82, v212, 16, 1
	v_bfe_i32 v145, v246, 16, 1
	v_exp_f32_e32 v74, v74
	v_exp_f32_e32 v158, v158
	v_and_b32_e32 v72, v82, v72
	v_and_b32_e32 v156, v145, v156
	v_bfe_i32 v113, v212, 17, 1
	v_bfe_i32 v198, v246, 17, 1
	v_exp_f32_e32 v75, v75
	v_exp_f32_e32 v159, v159
	v_and_b32_e32 v73, v113, v73
	v_and_b32_e32 v157, v198, v157
	v_add_f32_e32 v155, v155, v72
	v_add_f32_e32 v154, v154, v156
	v_bfe_i32 v82, v212, 18, 1
	v_bfe_i32 v145, v246, 18, 1
	v_and_b32_e32 v74, v82, v74
	v_and_b32_e32 v158, v145, v158
	v_add_f32_e32 v155, v155, v73
	v_add_f32_e32 v154, v154, v157
	v_bfe_i32 v113, v212, 19, 1
	v_bfe_i32 v198, v246, 19, 1
	v_and_b32_e32 v75, v113, v75
	v_and_b32_e32 v159, v198, v159
	v_add_f32_e32 v155, v155, v74
	v_add_f32_e32 v154, v154, v158
	v_add_f32_e32 v155, v155, v75
	v_add_f32_e32 v154, v154, v159
	v_cvt_pk_bf16_f32 v64, v64, v65
	v_cvt_pk_bf16_f32 v68, v68, v69
	v_cvt_pk_bf16_f32 v65, v66, v67
	v_cvt_pk_bf16_f32 v69, v70, v71
	v_cvt_pk_bf16_f32 v66, v72, v73
	v_cvt_pk_bf16_f32 v70, v156, v157
	v_cvt_pk_bf16_f32 v67, v74, v75
	v_cvt_pk_bf16_f32 v71, v158, v159
	v_exp_f32_e32 v160, v160
	v_exp_f32_e32 v182, v182
	v_mfma_f32_16x16x32_bf16 v[36:39], v[194:197], v[64:67], v[36:39]
	v_exp_f32_e32 v161, v161
	v_exp_f32_e32 v183, v183
	v_bfe_i32 v82, v213, 0, 1
	v_bfe_i32 v145, v247, 0, 1
	v_exp_f32_e32 v162, v162
	v_exp_f32_e32 v184, v184
	v_and_b32_e32 v160, v82, v160
	v_and_b32_e32 v182, v145, v182
	v_bfe_i32 v113, v213, 1, 1
	v_mfma_f32_16x16x32_bf16 v[32:35], v[194:197], v[68:71], v[32:35]
	v_bfe_i32 v198, v247, 1, 1
	v_exp_f32_e32 v163, v163
	v_exp_f32_e32 v185, v185
	v_and_b32_e32 v161, v113, v161
	v_and_b32_e32 v183, v198, v183
	v_add_f32_e32 v155, v155, v160
	v_add_f32_e32 v154, v154, v182
	v_bfe_i32 v82, v213, 2, 1
	v_bfe_i32 v145, v247, 2, 1
	v_mfma_f32_16x16x32_bf16 v[60:63], v[204:207], v[64:67], v[60:63]
	v_and_b32_e32 v162, v82, v162
	v_and_b32_e32 v184, v145, v184
	v_add_f32_e32 v155, v155, v161
	v_add_f32_e32 v154, v154, v183
	v_bfe_i32 v113, v213, 3, 1
	v_bfe_i32 v198, v247, 3, 1
	v_and_b32_e32 v163, v113, v163
	v_and_b32_e32 v185, v198, v185
	v_add_f32_e32 v155, v155, v162
	v_mfma_f32_16x16x32_bf16 v[52:55], v[204:207], v[68:71], v[52:55]
	v_add_f32_e32 v154, v154, v184
	v_add_f32_e32 v155, v155, v163
	v_add_f32_e32 v154, v154, v185
	v_exp_f32_e32 v186, v186
	v_exp_f32_e32 v190, v190
	v_exp_f32_e32 v187, v187
	v_exp_f32_e32 v191, v191
	v_bfe_i32 v82, v213, 16, 1
	v_bfe_i32 v145, v247, 16, 1
	v_mfma_f32_16x16x32_bf16 v[56:59], v[208:211], v[64:67], v[56:59]
	v_exp_f32_e32 v188, v188
	v_exp_f32_e32 v192, v192
	v_and_b32_e32 v186, v82, v186
	v_and_b32_e32 v190, v145, v190
	v_bfe_i32 v113, v213, 17, 1
	v_bfe_i32 v198, v247, 17, 1
	v_exp_f32_e32 v189, v189
	v_exp_f32_e32 v193, v193
	v_and_b32_e32 v187, v113, v187
	v_mfma_f32_16x16x32_bf16 v[44:47], v[208:211], v[68:71], v[44:47]
	v_and_b32_e32 v191, v198, v191
	v_add_f32_e32 v155, v155, v186
	v_add_f32_e32 v154, v154, v190
	v_bfe_i32 v82, v213, 18, 1
	v_bfe_i32 v145, v247, 18, 1
	v_and_b32_e32 v188, v82, v188
	v_and_b32_e32 v192, v145, v192
	v_add_f32_e32 v155, v155, v187
	v_add_f32_e32 v154, v154, v191
	v_mfma_f32_16x16x32_bf16 v[48:51], v[84:87], v[64:67], v[48:51]
	v_bfe_i32 v113, v213, 19, 1
	v_bfe_i32 v198, v247, 19, 1
	v_and_b32_e32 v189, v113, v189
	v_and_b32_e32 v193, v198, v193
	v_add_f32_e32 v155, v155, v188
	v_add_f32_e32 v154, v154, v192
	v_add_f32_e32 v155, v155, v189
	v_add_f32_e32 v154, v154, v193
	v_cvt_pk_bf16_f32 v160, v160, v161
	v_mfma_f32_16x16x32_bf16 v[40:43], v[84:87], v[68:71], v[40:43]
	v_cvt_pk_bf16_f32 v182, v182, v183
	v_cvt_pk_bf16_f32 v161, v162, v163
	v_cvt_pk_bf16_f32 v183, v184, v185
	v_cvt_pk_bf16_f32 v162, v186, v187
	v_cvt_pk_bf16_f32 v184, v190, v191
	v_cvt_pk_bf16_f32 v163, v188, v189
	v_cvt_pk_bf16_f32 v185, v192, v193
	s_add_i32 s39, s39, 1
	s_nop 0
	s_setprio 2
	v_mfma_f32_16x16x32_bf16 v[36:39], v[218:221], v[160:163], v[36:39]
	v_mfma_f32_16x16x32_bf16 v[32:35], v[218:221], v[182:185], v[32:35]
	v_mfma_f32_16x16x32_bf16 v[60:63], v[222:225], v[160:163], v[60:63]
	v_mfma_f32_16x16x32_bf16 v[52:55], v[222:225], v[182:185], v[52:55]
	v_mfma_f32_16x16x32_bf16 v[56:59], v[226:229], v[160:163], v[56:59]
	v_mfma_f32_16x16x32_bf16 v[44:47], v[226:229], v[182:185], v[44:47]
	v_mfma_f32_16x16x32_bf16 v[48:51], v[230:233], v[160:163], v[48:51]
	v_mfma_f32_16x16x32_bf16 v[40:43], v[230:233], v[182:185], v[40:43]
	s_cmp_lg_u32 s40, s39
	s_cbranch_scc1 .LBB0_885
	s_setprio 1
	v_lshlrev_b32_e32 v199, 4, v104
	ds_read_b128 v[84:87], v199 offset:54016
	s_waitcnt lgkmcnt(0)
	v_add_u32_e32 v0, s33, v171
	v_or_b32_e32 v0, s2, v0
	v_mov_b32_e32 v1, s3
	v_lshl_add_u64 v[2:3], v[0:1], 0, v[80:81]
	v_lshlrev_b64 v[2:3], 7, v[2:3]
	v_lshl_add_u64 v[2:3], v[142:143], 0, v[2:3]
	global_load_dwordx2 v[4:5], v[2:3], off
	global_load_dwordx2 v[6:7], v[2:3], off offset:32
	global_load_dwordx2 v[8:9], v[2:3], off offset:64
	v_and_b32_e32 v15, 64, v121
	global_load_dwordx2 v[2:3], v[2:3], off offset:96
	v_xor_b32_e32 v14, 16, v121
	v_add_u32_e32 v15, 64, v15
	v_cmp_lt_i32_e32 vcc, v14, v15
	s_waitcnt vmcnt(8)
	v_xor_b32_e32 v16, 32, v121
	v_lshl_add_u64 v[0:1], v[0:1], 0, v[76:77]
	v_cndmask_b32_e32 v14, v121, v14, vcc
	s_waitcnt vmcnt(7)
	v_lshlrev_b32_e32 v20, 2, v14
	ds_bpermute_b32 v14, v20, v155
	v_cmp_lt_i32_e32 vcc, v16, v15
	v_lshlrev_b64 v[0:1], 7, v[0:1]
	v_lshl_add_u64 v[0:1], v[142:143], 0, v[0:1]
	v_cndmask_b32_e32 v15, v121, v16, vcc
	v_lshlrev_b32_e32 v21, 2, v15
	s_waitcnt lgkmcnt(0)
	v_add_f32_e32 v14, v155, v14
	ds_bpermute_b32 v15, v21, v14
	v_readlane_b32 s48, v250, 24
	v_add_u32_e32 v10, s2, v80
	v_mov_b32_e32 v11, v117
	v_readlane_b32 s49, v250, 25
	s_waitcnt lgkmcnt(0)
	v_add_f32_e32 v22, v14, v15
	global_load_dwordx2 v[14:15], v[0:1], off
	global_load_dwordx2 v[16:17], v[0:1], off offset:32
	global_load_dwordx2 v[18:19], v[0:1], off offset:64
	s_nop 0
	global_load_dwordx2 v[0:1], v[0:1], off offset:96
	v_div_scale_f32 v23, s[38:39], v22, v22, 1.0
	s_waitcnt vmcnt(9)
	v_rcp_f32_e32 v24, v23
	v_div_scale_f32 v25, vcc, 1.0, v22, 1.0
	v_readlane_b32 s60, v250, 36
	v_fma_f32 v26, -v23, v24, 1.0
	v_fmac_f32_e32 v24, v26, v24
	v_mul_f32_e32 v26, v25, v24
	v_fma_f32 v27, -v23, v26, v25
	v_fmac_f32_e32 v26, v27, v24
	v_fma_f32 v23, -v23, v26, v25
	v_div_fmas_f32 v23, v23, v24, v26
	v_readlane_b32 s61, v250, 37
	v_div_fixup_f32 v23, v23, v22, 1.0
	v_cmp_lt_f32_e32 vcc, 0, v22
	v_readlane_b32 s3, v248, 12
	v_lshlrev_b64 v[10:11], 11, v[10:11]
	s_mov_b64 s[48:49], s[60:61]
	v_cndmask_b32_e32 v22, 0, v23, vcc
	v_lshl_or_b32 v12, s3, 9, v179
	v_mov_b32_e32 v13, v117
	v_lshl_add_u64 v[10:11], s[48:49], 0, v[10:11]
	v_mul_f32_e32 v23, v36, v22
	v_mul_f32_e32 v24, v37, v22
	v_mul_f32_e32 v26, v39, v22
	v_mov_b32_e32 v145, v117
	v_lshl_add_u64 v[10:11], v[10:11], 0, v[12:13]
	v_mul_f32_e32 v25, v38, v22
	s_waitcnt vmcnt(8)
	v_mul_f32_e32 v28, v61, v22
	v_mul_f32_e32 v30, v63, v22
	v_lshl_add_u64 v[10:11], v[10:11], 0, v[144:145]
	v_mul_f32_e32 v27, v60, v22
	v_mul_f32_e32 v29, v62, v22
	v_mul_f32_e32 v31, v56, v22
	v_readlane_b32 s50, v250, 26
	v_readlane_b32 s51, v250, 27
	v_readlane_b32 s60, v250, 56
	v_readlane_b32 s61, v250, 57
	v_readlane_b32 s50, v248, 20
	v_readlane_b32 s51, v248, 21
	v_readlane_b32 s52, v250, 28
	v_readlane_b32 s53, v250, 29
	v_readlane_b32 s54, v250, 30
	v_readlane_b32 s55, v250, 31
	v_readlane_b32 s56, v250, 32
	v_readlane_b32 s57, v250, 33
	v_readlane_b32 s58, v250, 34
	v_readlane_b32 s59, v250, 35
	v_readlane_b32 s62, v250, 38
	v_readlane_b32 s63, v250, 39
	s_waitcnt vmcnt(7)
	v_lshlrev_b32_e32 v36, 16, v4
	v_and_b32_e32 v4, 0xffff0000, v4
	v_lshlrev_b32_e32 v37, 16, v5
	v_and_b32_e32 v5, 0xffff0000, v5
	s_waitcnt vmcnt(6)
	v_lshlrev_b32_e32 v38, 16, v6
	v_and_b32_e32 v6, 0xffff0000, v6
	v_lshlrev_b32_e32 v39, 16, v7
	v_and_b32_e32 v7, 0xffff0000, v7
	v_mul_f32_e32 v4, v24, v4
	v_mul_f32_e32 v5, v26, v5
	v_mul_f32_e32 v23, v23, v36
	v_mul_f32_e32 v24, v25, v37
	v_mul_f32_e32 v6, v28, v6
	v_mul_f32_e32 v7, v30, v7
	v_cvt_pk_bf16_f32 v4, v23, v4
	v_cvt_pk_bf16_f32 v5, v24, v5
	v_mul_f32_e32 v25, v27, v38
	v_mul_f32_e32 v26, v29, v39
	v_cvt_pk_bf16_f32 v6, v25, v6
	v_cvt_pk_bf16_f32 v7, v26, v7
	global_store_dwordx2 v[10:11], v[4:5], off offset:1024 sc1
	global_store_dwordx2 v[10:11], v[6:7], off offset:1056 sc1
	v_mul_f32_e32 v4, v57, v22
	s_waitcnt vmcnt(7)
	v_and_b32_e32 v5, 0xffff0000, v8
	v_mul_f32_e32 v4, v4, v5
	v_mul_f32_e32 v5, v58, v22
	v_lshlrev_b32_e32 v6, 16, v9
	v_mul_f32_e32 v5, v5, v6
	v_mul_f32_e32 v6, v59, v22
	v_and_b32_e32 v7, 0xffff0000, v9
	v_mul_f32_e32 v6, v6, v7
	v_cvt_pk_bf16_f32 v5, v5, v6
	ds_bpermute_b32 v6, v20, v154
	v_lshlrev_b32_e32 v56, 16, v8
	v_mul_f32_e32 v27, v31, v56
	v_cvt_pk_bf16_f32 v4, v27, v4
	global_store_dwordx2 v[10:11], v[4:5], off offset:1088 sc1
	v_mul_f32_e32 v4, v48, v22
	s_waitcnt vmcnt(7)
	v_lshlrev_b32_e32 v5, 16, v2
	v_mul_f32_e32 v4, v4, v5
	v_mul_f32_e32 v5, v49, v22
	v_and_b32_e32 v2, 0xffff0000, v2
	v_mul_f32_e32 v2, v5, v2
	s_waitcnt lgkmcnt(0)
	v_add_f32_e32 v5, v154, v6
	ds_bpermute_b32 v6, v21, v5
	v_cvt_pk_bf16_f32 v2, v4, v2
	v_mul_f32_e32 v4, v50, v22
	v_lshlrev_b32_e32 v7, 16, v3
	v_mul_f32_e32 v4, v4, v7
	s_waitcnt lgkmcnt(0)
	v_add_f32_e32 v5, v5, v6
	v_div_scale_f32 v6, s[38:39], v5, v5, 1.0
	v_rcp_f32_e32 v8, v6
	v_mul_f32_e32 v7, v51, v22
	v_and_b32_e32 v3, 0xffff0000, v3
	v_mul_f32_e32 v3, v7, v3
	v_cvt_pk_bf16_f32 v3, v4, v3
	global_store_dwordx2 v[10:11], v[2:3], off offset:1120 sc1
	v_fma_f32 v2, -v6, v8, 1.0
	v_fmac_f32_e32 v8, v2, v8
	v_div_scale_f32 v2, vcc, 1.0, v5, 1.0
	v_mul_f32_e32 v3, v2, v8
	v_fma_f32 v4, -v6, v3, v2
	v_fmac_f32_e32 v3, v4, v8
	v_fma_f32 v2, -v6, v3, v2
	v_div_fmas_f32 v2, v2, v8, v3
	v_div_fixup_f32 v2, v2, v5, 1.0
	v_cmp_lt_f32_e32 vcc, 0, v5
	s_waitcnt vmcnt(7)
	v_lshlrev_b32_e32 v5, 16, v14
	v_mov_b32_e32 v3, v117
	v_cndmask_b32_e32 v6, 0, v2, vcc
	v_mul_f32_e32 v4, v32, v6
	v_add_u32_e32 v2, s2, v76
	v_mul_f32_e32 v4, v4, v5
	v_mul_f32_e32 v5, v33, v6
	v_and_b32_e32 v7, 0xffff0000, v14
	v_lshlrev_b64 v[2:3], 11, v[2:3]
	v_mul_f32_e32 v5, v5, v7
	v_lshl_add_u64 v[2:3], s[48:49], 0, v[2:3]
	v_cvt_pk_bf16_f32 v4, v4, v5
	v_mul_f32_e32 v5, v34, v6
	v_lshlrev_b32_e32 v7, 16, v15
	v_lshl_add_u64 v[2:3], v[2:3], 0, v[12:13]
	v_mul_f32_e32 v5, v5, v7
	v_mul_f32_e32 v7, v35, v6
	v_and_b32_e32 v8, 0xffff0000, v15
	v_lshl_add_u64 v[2:3], v[2:3], 0, v[144:145]
	v_mul_f32_e32 v7, v7, v8
	v_cvt_pk_bf16_f32 v5, v5, v7
	global_store_dwordx2 v[2:3], v[4:5], off offset:1024 sc1
	v_mul_f32_e32 v4, v52, v6
	s_waitcnt vmcnt(7)
	v_lshlrev_b32_e32 v5, 16, v16
	v_mul_f32_e32 v4, v4, v5
	v_mul_f32_e32 v5, v53, v6
	v_and_b32_e32 v7, 0xffff0000, v16
	v_mul_f32_e32 v5, v5, v7
	v_cvt_pk_bf16_f32 v4, v4, v5
	v_mul_f32_e32 v5, v54, v6
	v_lshlrev_b32_e32 v7, 16, v17
	v_mul_f32_e32 v5, v5, v7
	v_mul_f32_e32 v7, v55, v6
	v_and_b32_e32 v8, 0xffff0000, v17
	v_mul_f32_e32 v7, v7, v8
	v_cvt_pk_bf16_f32 v5, v5, v7
	global_store_dwordx2 v[2:3], v[4:5], off offset:1056 sc1
	v_mul_f32_e32 v4, v44, v6
	s_waitcnt vmcnt(7)
	v_lshlrev_b32_e32 v5, 16, v18
	v_mul_f32_e32 v4, v4, v5
	v_mul_f32_e32 v5, v45, v6
	v_and_b32_e32 v7, 0xffff0000, v18
	v_mul_f32_e32 v5, v5, v7
	v_cvt_pk_bf16_f32 v4, v4, v5
	v_mul_f32_e32 v5, v46, v6
	v_lshlrev_b32_e32 v7, 16, v19
	v_mul_f32_e32 v5, v5, v7
	v_mul_f32_e32 v7, v47, v6
	v_and_b32_e32 v8, 0xffff0000, v19
	v_mul_f32_e32 v7, v7, v8
	v_cvt_pk_bf16_f32 v5, v5, v7
	global_store_dwordx2 v[2:3], v[4:5], off offset:1088 sc1
	v_mul_f32_e32 v4, v40, v6
	s_waitcnt vmcnt(7)
	v_lshlrev_b32_e32 v5, 16, v0
	v_mul_f32_e32 v4, v4, v5
	v_mul_f32_e32 v5, v41, v6
	v_and_b32_e32 v0, 0xffff0000, v0
	v_mul_f32_e32 v0, v5, v0
	v_cvt_pk_bf16_f32 v0, v4, v0
	v_mul_f32_e32 v4, v42, v6
	v_lshlrev_b32_e32 v5, 16, v1
	v_mul_f32_e32 v4, v4, v5
	v_mul_f32_e32 v5, v43, v6
	v_and_b32_e32 v1, 0xffff0000, v1
	v_mul_f32_e32 v1, v5, v1
	v_cvt_pk_bf16_f32 v1, v4, v1
	global_store_dwordx2 v[2:3], v[0:1], off offset:1120 sc1
	s_waitcnt vmcnt(0)
	s_mov_b64 s[2:3], s[60:61]
	s_barrier
